# combined: staged epilogue waits + FoX diagonal-test and tile back-edge branch trims on top of v64
# speedup vs baseline: 1.0076x; 1.0076x over previous
.LBB0_250:
	s_cmp_eq_u64 s[8:9], 0
	s_mov_b32 s12, 1
	s_mov_b64 s[8:9], 0
	s_cbranch_scc1 .LBB0_242
